# prompt attention selection mask: both s_nop 0 per element removed (8 bytes per element, 8-byte phase of the rest of the loop unchanged)
# baseline (speedup 1.0000x reference)
.LBB0_1900:
	s_lshl_b32 s56, s8, 8
	s_or_b32 s4, s20, s56
	s_lshl_b32 s5, s52, 5
	s_add_u32 s4, s4, s5
	s_addc_u32 s5, s21, 0
	s_and_b32 s53, s7, 0x3fffffc0
	s_lshl_b32 s22, s52, 4
	s_lshl_b32 s57, s52, 10
	s_cmp_lg_u32 0, -1
	s_cselect_b32 s8, 0, 0
	s_add_i32 s57, s57, s8
	s_add_i32 s59, s56, 0x100
	s_lshl_b64 s[4:5], s[4:5], 11
	v_and_or_b32 v2, s22, 48, v101
	s_add_u32 s40, s47, s4
	s_addc_u32 s41, s48, s5
	v_lshlrev_b32_e32 v2, 9, v2
	s_lshr_b32 s4, s7, 2
	v_lshl_add_u64 v[220:221], v[200:201], 0, s[22:23]
	v_lshl_add_u64 v[4:5], s[24:25], 0, v[2:3]
	s_and_b32 s22, s4, 0x3fffffc0
	s_waitcnt vmcnt(0) lgkmcnt(0)
	v_lshl_add_u64 v[4:5], v[4:5], 0, s[22:23]
	v_mov_b32_e32 v217, v3
	s_mov_b32 s4, m0
	s_mov_b32 m0, s57
	s_nop 0
	global_load_lds_dwordx4 v[220:221], off
	s_mov_b32 m0, s4
	v_lshl_add_u64 v[222:223], v[4:5], 0, v[216:217]
	s_add_i32 s58, s57, 0x6000
	s_mov_b32 s4, m0
	s_mov_b32 m0, s58
	s_nop 0
	global_load_lds_dwordx4 v[222:223], off
	s_mov_b32 m0, s4
	v_lshl_add_u64 v[4:5], v[220:221], 0, s[26:27]
	s_add_i32 s4, s57, 0x2000
	s_mov_b32 s5, m0
	s_mov_b32 m0, s4
	s_nop 0
	global_load_lds_dwordx4 v[4:5], off
	s_mov_b32 m0, s5
	v_lshl_add_u64 v[4:5], s[40:41], 0, v[202:203]
	v_mov_b32_e32 v219, v3
	v_lshl_add_u64 v[4:5], v[4:5], 0, v[218:219]
	global_load_dwordx4 v[130:133], v[4:5], off
	global_load_dwordx4 v[126:129], v[4:5], off offset:32
	global_load_dwordx4 v[122:125], v[4:5], off offset:64
	global_load_dwordx4 v[114:117], v[4:5], off offset:96
	v_lshl_add_u64 v[4:5], v[220:221], 0, s[28:29]
	s_add_i32 s4, s57, 0x4000
	s_mov_b32 s5, m0
	s_mov_b32 m0, s4
	s_nop 0
	global_load_lds_dwordx4 v[4:5], off
	s_mov_b32 m0, s5
	s_waitcnt vmcnt(3) lgkmcnt(0)
	s_barrier
	ds_read_b128 v[4:7], v235
	ds_read_b128 v[20:23], v235 offset:512
	ds_read_b128 v[36:39], v235 offset:2048
	v_add3_u32 v209, s6, v249, v243
	s_lshl_b32 s22, s53, 2
	s_add_i32 s53, s22, 0
	s_mov_b32 s4, 0
	s_movk_i32 s60, 0x2000
	s_movk_i32 s62, 0x4000
	s_lshr_b32 s59, s59, 6
	s_mov_b32 s22, 1
	v_lshl_add_u32 v207, v100, 2, s53
	s_waitcnt vmcnt(3) lgkmcnt(2)
	v_mfma_f32_32x32x16_bf16 v[4:19], v[4:7], v[130:133], 0
	s_waitcnt vmcnt(2) lgkmcnt(0)
	v_mfma_f32_32x32x16_bf16 v[4:19], v[36:39], v[126:129], v[4:19]
	ds_read_b128 v[36:39], v235 offset:2560
	v_mfma_f32_32x32x16_bf16 v[20:35], v[20:23], v[130:133], 0
	s_waitcnt lgkmcnt(0)
	v_mfma_f32_32x32x16_bf16 v[20:35], v[36:39], v[126:129], v[20:35]
	ds_read_b128 v[36:39], v235 offset:4096
	ds_read_b128 v[40:43], v235 offset:4608
	s_waitcnt vmcnt(1) lgkmcnt(1)
	v_mfma_f32_32x32x16_bf16 v[4:19], v[36:39], v[122:125], v[4:19]
	ds_read_b128 v[36:39], v235 offset:6656
	ds_read_b128 v[44:47], v235 offset:6144
	s_waitcnt lgkmcnt(2)
	v_mfma_f32_32x32x16_bf16 v[20:35], v[40:43], v[122:125], v[20:35]
	s_waitcnt vmcnt(0) lgkmcnt(0)
	v_mfma_f32_32x32x16_bf16 v[4:19], v[44:47], v[114:117], v[4:19]
	v_mfma_f32_32x32x16_bf16 v[20:35], v[36:39], v[114:117], v[20:35]
	s_nop 15
	s_nop 7
	ds_read_b32 v2, v209
	s_waitcnt lgkmcnt(0)
	v_bfe_i32 v36, v2, 0, 1
	v_bfi_b32 v4, v36, s49, v4
	s_waitcnt vmcnt(0) lgkmcnt(0)
	s_barrier
	v_bfe_i32 v36, v2, 1, 1
	v_bfi_b32 v5, v36, s49, v5
	v_bfe_i32 v36, v2, 2, 1
	v_bfi_b32 v6, v36, s49, v6
	v_bfe_i32 v36, v2, 3, 1
	v_bfi_b32 v7, v36, s49, v7
	v_bfe_i32 v36, v2, 4, 1
	v_bfi_b32 v8, v36, s49, v8
	v_bfe_i32 v36, v2, 5, 1
	v_bfi_b32 v9, v36, s49, v9
	v_bfe_i32 v36, v2, 6, 1
	v_bfi_b32 v10, v36, s49, v10
	v_bfe_i32 v36, v2, 7, 1
	v_bfi_b32 v11, v36, s49, v11
	v_bfe_i32 v36, v2, 8, 1
	v_bfi_b32 v12, v36, s49, v12
	v_bfe_i32 v36, v2, 9, 1
	v_bfi_b32 v13, v36, s49, v13
	v_bfe_i32 v36, v2, 10, 1
	v_bfi_b32 v14, v36, s49, v14
	v_bfe_i32 v36, v2, 11, 1
	v_bfi_b32 v15, v36, s49, v15
	v_bfe_i32 v36, v2, 12, 1
	v_bfi_b32 v16, v36, s49, v16
	v_bfe_i32 v36, v2, 13, 1
	v_bfi_b32 v17, v36, s49, v17
	v_bfe_i32 v36, v2, 14, 1
	v_bfi_b32 v18, v36, s49, v18
	v_bfe_i32 v36, v2, 15, 1
	v_bfi_b32 v19, v36, s49, v19
	v_bfe_i32 v36, v2, 16, 1
	v_bfi_b32 v20, v36, s49, v20
	v_bfe_i32 v36, v2, 17, 1
	v_bfi_b32 v21, v36, s49, v21
	v_bfe_i32 v36, v2, 18, 1
	v_bfi_b32 v22, v36, s49, v22
	v_bfe_i32 v36, v2, 19, 1
	v_bfi_b32 v23, v36, s49, v23
	v_bfe_i32 v36, v2, 20, 1
	v_bfi_b32 v24, v36, s49, v24
	v_bfe_i32 v36, v2, 21, 1
	v_bfi_b32 v25, v36, s49, v25
	v_bfe_i32 v36, v2, 22, 1
	v_bfi_b32 v26, v36, s49, v26
	v_bfe_i32 v36, v2, 23, 1
	v_bfi_b32 v27, v36, s49, v27
	v_bfe_i32 v36, v2, 24, 1
	v_bfi_b32 v28, v36, s49, v28
	v_bfe_i32 v36, v2, 25, 1
	v_bfi_b32 v29, v36, s49, v29
	v_bfe_i32 v36, v2, 26, 1
	v_bfi_b32 v30, v36, s49, v30
	v_bfe_i32 v36, v2, 27, 1
	v_bfi_b32 v31, v36, s49, v31
	v_bfe_i32 v36, v2, 28, 1
	v_bfi_b32 v32, v36, s49, v32
	v_bfe_i32 v36, v2, 29, 1
	v_bfi_b32 v33, v36, s49, v33
	v_bfe_i32 v36, v2, 30, 1
	v_bfi_b32 v34, v36, s49, v34
	v_bfe_i32 v36, v2, 31, 1
	v_bfi_b32 v35, v36, s49, v35
	s_nop 0
	v_max3_f32 v2, v4, v5, v20
	s_nop 0
	v_max3_f32 v36, v6, v7, v21
	v_max3_f32 v2, v2, v22, v23
	s_nop 0
	v_max3_f32 v36, v36, v10, v11
	v_max3_f32 v2, v2, v8, v9
	s_nop 0
	v_max3_f32 v36, v36, v26, v27
	v_max3_f32 v2, v2, v24, v25
	s_nop 0
	v_max3_f32 v36, v36, v14, v15
	v_max3_f32 v2, v2, v12, v13
	s_nop 0
	v_max3_f32 v36, v36, v30, v31
	v_max3_f32 v2, v2, v28, v29
	s_nop 0
	v_max3_f32 v36, v36, v18, v19
	v_max3_f32 v2, v2, v16, v17
	s_nop 0
	v_max3_f32 v36, v36, v34, v35
	v_max3_f32 v2, v2, v32, v33
	s_nop 0
	v_max_f32_e32 v2, v2, v36
	s_nop 0
	v_mov_b32_e32 v36, v2
	s_nop 1
	v_permlane32_swap_b32_e32 v2, v36
	v_max_f32_e32 v2, v2, v36
	s_nop 0
	v_cmp_ngt_f32_e32 vcc, s50, v2
	s_nop 1
	v_cndmask_b32_e32 v2, 0, v2, vcc
	v_sub_f32_e32 v4, v4, v2
	v_sub_f32_e32 v5, v5, v2
	v_add_f32_e32 v211, v3, v2
	v_sub_f32_e32 v20, v20, v2
	v_sub_f32_e32 v21, v21, v2
	v_sub_f32_e32 v6, v6, v2
	s_nop 0
	v_exp_f32_e32 v52, v4
	v_exp_f32_e32 v53, v5
	v_lshl_add_u64 v[4:5], v[220:221], 0, s[30:31]
	s_mov_b32 s63, m0
	s_mov_b32 m0, s57
	s_nop 0
	global_load_lds_dwordx4 v[4:5], off
	s_mov_b32 m0, s63
	v_lshl_add_u64 v[4:5], v[222:223], 0, s[26:27]
	s_add_i32 s63, s57, 0x8000
	s_mov_b32 s64, m0
	s_mov_b32 m0, s63
	s_nop 0
	global_load_lds_dwordx4 v[4:5], off
	s_mov_b32 m0, s64
	ds_read_b128 v[162:165], v235 offset:8192
	ds_read_b128 v[158:161], v235 offset:8704
	ds_read_b128 v[154:157], v235 offset:10240
	ds_read_b128 v[150:153], v235 offset:10752
	ds_read_b128 v[146:149], v235 offset:12288
	ds_read_b128 v[142:145], v235 offset:12800
	ds_read_b128 v[138:141], v235 offset:14336
	ds_read_b128 v[134:137], v235 offset:14848
	v_sub_f32_e32 v22, v22, v2
	v_sub_f32_e32 v7, v7, v2
	v_sub_f32_e32 v23, v23, v2
	v_sub_f32_e32 v8, v8, v2
	v_sub_f32_e32 v24, v24, v2
	v_sub_f32_e32 v9, v9, v2
	v_sub_f32_e32 v25, v25, v2
	v_sub_f32_e32 v10, v10, v2
	v_sub_f32_e32 v26, v26, v2
	v_sub_f32_e32 v11, v11, v2
	v_sub_f32_e32 v27, v27, v2
	v_sub_f32_e32 v12, v12, v2
	v_sub_f32_e32 v28, v28, v2
	v_sub_f32_e32 v13, v13, v2
	v_sub_f32_e32 v29, v29, v2
	v_sub_f32_e32 v14, v14, v2
	v_sub_f32_e32 v30, v30, v2
	v_sub_f32_e32 v15, v15, v2
	v_sub_f32_e32 v31, v31, v2
	v_sub_f32_e32 v16, v16, v2
	v_sub_f32_e32 v32, v32, v2
	v_sub_f32_e32 v17, v17, v2
	v_sub_f32_e32 v33, v33, v2
	v_sub_f32_e32 v18, v18, v2
	v_sub_f32_e32 v34, v34, v2
	v_sub_f32_e32 v19, v19, v2
	v_sub_f32_e32 v2, v35, v2
	v_exp_f32_e32 v54, v6
	v_exp_f32_e32 v55, v7
	v_exp_f32_e32 v56, v8
	v_exp_f32_e32 v57, v9
	v_exp_f32_e32 v58, v10
	v_exp_f32_e32 v59, v11
	v_exp_f32_e32 v60, v12
	v_exp_f32_e32 v61, v13
	v_exp_f32_e32 v62, v14
	v_exp_f32_e32 v63, v15
	v_exp_f32_e32 v64, v16
	v_exp_f32_e32 v65, v17
	v_exp_f32_e32 v66, v18
	v_exp_f32_e32 v67, v19
	v_exp_f32_e32 v36, v20
	v_exp_f32_e32 v37, v21
	v_exp_f32_e32 v38, v22
	v_exp_f32_e32 v39, v23
	v_exp_f32_e32 v40, v24
	v_exp_f32_e32 v41, v25
	v_exp_f32_e32 v42, v26
	v_exp_f32_e32 v43, v27
	v_exp_f32_e32 v44, v28
	v_exp_f32_e32 v45, v29
	v_exp_f32_e32 v46, v30
	v_exp_f32_e32 v47, v31
	v_exp_f32_e32 v48, v32
	v_exp_f32_e32 v49, v33
	v_exp_f32_e32 v50, v34
	v_exp_f32_e32 v51, v2
	s_waitcnt vmcnt(2) lgkmcnt(0)
	s_barrier
	s_andn2_b64 vcc, exec, s[42:43]
	s_cbranch_vccnz .LBB0_1962
	v_mov_b32_e32 v16, v3
	v_mov_b32_e32 v17, v3
	v_mov_b32_e32 v2, v3
	v_mov_b32_e32 v4, v3
	v_mov_b32_e32 v5, v3
	v_mov_b32_e32 v6, v3
	v_mov_b32_e32 v7, v3
	v_mov_b32_e32 v8, v3
	v_mov_b32_e32 v9, v3
	v_mov_b32_e32 v10, v3
	v_mov_b32_e32 v11, v3
	v_mov_b32_e32 v12, v3
	v_mov_b32_e32 v13, v3
	v_mov_b32_e32 v14, v3
	v_mov_b32_e32 v15, v3
	v_mov_b64_e32 v[34:35], v[16:17]
	v_mov_b64_e32 v[32:33], v[14:15]
	v_mov_b64_e32 v[30:31], v[12:13]
	v_mov_b64_e32 v[28:29], v[10:11]
	v_mov_b64_e32 v[26:27], v[8:9]
	v_mov_b64_e32 v[24:25], v[6:7]
	v_mov_b64_e32 v[22:23], v[4:5]
	v_mov_b64_e32 v[20:21], v[2:3]
	v_mov_b64_e32 v[18:19], v[16:17]
	v_add_u32_e32 v182, s61, v244
	s_mov_b32 s8, 0
	s_movk_i32 s4, 0x4000
	s_movk_i32 s12, 0x2000
	v_mov_b32_e32 v213, 0
	s_mov_b32 s5, 6
	s_mov_b64 s[6:7], 0
	v_mov_b64_e32 v[16:17], v[14:15]
	v_mov_b64_e32 v[14:15], v[12:13]
	v_mov_b64_e32 v[12:13], v[10:11]
	v_mov_b64_e32 v[10:11], v[8:9]
	v_mov_b64_e32 v[8:9], v[6:7]
	v_mov_b64_e32 v[6:7], v[4:5]
	v_mov_b64_e32 v[4:5], v[2:3]
.LBB0_1902:
	v_add_u32_e32 v2, s8, v199
	ds_read_b64_tr_b16 v[166:167], v2 offset:24576
	ds_read_b64_tr_b16 v[168:169], v2 offset:25088
	v_add_f32_e32 v68, v52, v53
	v_add_f32_e32 v68, v54, v68
	v_add_f32_e32 v68, v55, v68
	v_add_f32_e32 v68, v56, v68
	v_add_f32_e32 v84, v57, v68
	s_waitcnt lgkmcnt(9)
	v_mfma_f32_32x32x16_bf16 v[68:83], v[162:165], v[130:133], 0
	v_cvt_pk_bf16_f32 v118, v52, v53
	v_cvt_pk_bf16_f32 v119, v54, v55
	ds_read_b64_tr_b16 v[162:163], v2 offset:28672
	ds_read_b64_tr_b16 v[164:165], v2 offset:29184
	v_add_f32_e32 v52, v58, v84
	v_add_f32_e32 v52, v59, v52
	v_add_f32_e32 v52, v60, v52
	v_add_f32_e32 v52, v61, v52
	v_cvt_pk_bf16_f32 v120, v56, v57
	v_cvt_pk_bf16_f32 v121, v58, v59
	s_waitcnt lgkmcnt(10)
	v_mfma_f32_32x32x16_bf16 v[84:99], v[158:161], v[130:133], 0
	ds_read_b64_tr_b16 v[158:159], v2 offset:25600
	ds_read_b64_tr_b16 v[160:161], v2 offset:26112
	s_waitcnt lgkmcnt(11)
	v_mfma_f32_32x32x16_bf16 v[68:83], v[154:157], v[126:129], v[68:83]
	v_add_f32_e32 v52, v62, v52
	v_add_f32_e32 v52, v63, v52
	v_add_f32_e32 v52, v64, v52
	v_add_f32_e32 v52, v65, v52
	v_cvt_pk_bf16_f32 v110, v60, v61
	v_cvt_pk_bf16_f32 v111, v62, v63
	ds_read_b64_tr_b16 v[154:155], v2 offset:29696
	ds_read_b64_tr_b16 v[156:157], v2 offset:30208
	v_add_f32_e32 v52, v66, v52
	v_add_f32_e32 v52, v67, v52
	v_add_f32_e32 v52, v36, v52
	v_add_f32_e32 v52, v37, v52
	v_cvt_pk_bf16_f32 v112, v64, v65
	v_cvt_pk_bf16_f32 v113, v66, v67
	s_waitcnt lgkmcnt(12)
	v_mfma_f32_32x32x16_bf16 v[84:99], v[150:153], v[126:129], v[84:99]
	ds_read_b64_tr_b16 v[150:151], v2 offset:26624
	ds_read_b64_tr_b16 v[152:153], v2 offset:27136
	s_waitcnt lgkmcnt(13)
	v_mfma_f32_32x32x16_bf16 v[68:83], v[146:149], v[122:125], v[68:83]
	v_add_f32_e32 v52, v38, v52
	v_add_f32_e32 v52, v39, v52
	v_add_f32_e32 v52, v40, v52
	v_add_f32_e32 v52, v41, v52
	v_cvt_pk_bf16_f32 v106, v36, v37
	v_cvt_pk_bf16_f32 v107, v38, v39
	ds_read_b64_tr_b16 v[146:147], v2 offset:30720
	ds_read_b64_tr_b16 v[148:149], v2 offset:31232
	v_add_f32_e32 v36, v42, v52
	v_add_f32_e32 v36, v43, v36
	v_add_f32_e32 v36, v44, v36
	v_add_f32_e32 v36, v45, v36
	v_cvt_pk_bf16_f32 v108, v40, v41
	v_cvt_pk_bf16_f32 v109, v42, v43
	s_waitcnt lgkmcnt(14)
	v_mfma_f32_32x32x16_bf16 v[84:99], v[142:145], v[122:125], v[84:99]
	ds_read_b64_tr_b16 v[142:143], v2 offset:27648
	ds_read_b64_tr_b16 v[144:145], v2 offset:28160
	s_waitcnt lgkmcnt(14)
	v_mfma_f32_32x32x16_bf16 v[68:83], v[138:141], v[114:117], v[68:83]
	v_add_f32_e32 v36, v46, v36
	v_add_f32_e32 v36, v47, v36
	v_add_f32_e32 v36, v48, v36
	v_add_f32_e32 v36, v49, v36
	v_cvt_pk_bf16_f32 v102, v44, v45
	v_cvt_pk_bf16_f32 v103, v46, v47
	ds_read_b64_tr_b16 v[138:139], v2 offset:31744
	ds_read_b64_tr_b16 v[140:141], v2 offset:32256
	v_add_f32_e32 v2, v50, v36
	v_add_f32_e32 v2, v51, v2
	v_add_f32_e32 v2, 0, v2
	v_cvt_pk_bf16_f32 v104, v48, v49
	v_cvt_pk_bf16_f32 v105, v50, v51
	v_mfma_f32_32x32x16_bf16 v[84:99], v[134:137], v[114:117], v[84:99]
	v_lshl_add_u64 v[178:179], v[220:221], 0, s[6:7]
	v_lshl_add_u64 v[36:37], v[178:179], 0, s[34:35]
	v_lshl_add_u64 v[180:181], v[222:223], 0, s[6:7]
	s_add_i32 s8, s12, s57
	s_mov_b32 s9, m0
	s_mov_b32 m0, s8
	s_nop 0
	global_load_lds_dwordx4 v[36:37], off
	s_mov_b32 m0, s9
	v_lshl_add_u64 v[36:37], v[180:181], 0, s[28:29]
	s_add_i32 s8, s4, s58
	s_mov_b32 s9, m0
	s_mov_b32 m0, s8
	s_nop 0
	global_load_lds_dwordx4 v[36:37], off
	s_mov_b32 m0, s9
	v_sub_f32_e32 v52, v68, v211
	s_nop 4
	v_sub_f32_e32 v36, v84, v211
	v_sub_f32_e32 v53, v69, v211
	v_sub_f32_e32 v37, v85, v211
	v_sub_f32_e32 v54, v70, v211
	v_sub_f32_e32 v38, v86, v211
	v_sub_f32_e32 v55, v71, v211
	v_sub_f32_e32 v39, v87, v211
	v_sub_f32_e32 v56, v72, v211
	v_sub_f32_e32 v40, v88, v211
	v_sub_f32_e32 v57, v73, v211
	v_sub_f32_e32 v41, v89, v211
	v_sub_f32_e32 v58, v74, v211
	v_sub_f32_e32 v42, v90, v211
	v_sub_f32_e32 v59, v75, v211
	v_sub_f32_e32 v43, v91, v211
	v_sub_f32_e32 v60, v76, v211
	v_sub_f32_e32 v44, v92, v211
	v_sub_f32_e32 v61, v77, v211
	v_sub_f32_e32 v45, v93, v211
	v_sub_f32_e32 v62, v78, v211
	v_sub_f32_e32 v46, v94, v211
	v_sub_f32_e32 v63, v79, v211
	v_sub_f32_e32 v47, v95, v211
	v_sub_f32_e32 v64, v80, v211
	v_sub_f32_e32 v48, v96, v211
	v_sub_f32_e32 v65, v81, v211
	v_sub_f32_e32 v49, v97, v211
	v_sub_f32_e32 v66, v82, v211
	v_sub_f32_e32 v50, v98, v211
	v_sub_f32_e32 v67, v83, v211
	v_sub_f32_e32 v51, v99, v211
	ds_read_b32 v68, v182
	s_waitcnt lgkmcnt(0)
	v_bfe_i32 v69, v68, 0, 1
	v_bfi_b32 v52, v69, s49, v52
	s_nop 0
	v_add_f32_e32 v2, v213, v2
	v_bfe_i32 v69, v68, 1, 1
	v_bfi_b32 v53, v69, s49, v53
	v_bfe_i32 v69, v68, 2, 1
	v_bfi_b32 v54, v69, s49, v54
	v_bfe_i32 v69, v68, 3, 1
	v_bfi_b32 v55, v69, s49, v55
	v_bfe_i32 v69, v68, 4, 1
	v_bfi_b32 v56, v69, s49, v56
	v_bfe_i32 v69, v68, 5, 1
	v_bfi_b32 v57, v69, s49, v57
	v_bfe_i32 v69, v68, 6, 1
	v_bfi_b32 v58, v69, s49, v58
	v_bfe_i32 v69, v68, 7, 1
	v_bfi_b32 v59, v69, s49, v59
	v_bfe_i32 v69, v68, 8, 1
	v_bfi_b32 v60, v69, s49, v60
	v_bfe_i32 v69, v68, 9, 1
	v_bfi_b32 v61, v69, s49, v61
	v_bfe_i32 v69, v68, 10, 1
	v_bfi_b32 v62, v69, s49, v62
	v_bfe_i32 v69, v68, 11, 1
	v_bfi_b32 v63, v69, s49, v63
	v_bfe_i32 v69, v68, 12, 1
	v_bfi_b32 v64, v69, s49, v64
	v_bfe_i32 v69, v68, 13, 1
	v_bfi_b32 v65, v69, s49, v65
	v_bfe_i32 v69, v68, 14, 1
	v_bfi_b32 v66, v69, s49, v66
	v_bfe_i32 v69, v68, 15, 1
	v_bfi_b32 v67, v69, s49, v67
	v_bfe_i32 v69, v68, 16, 1
	v_bfi_b32 v36, v69, s49, v36
	v_bfe_i32 v69, v68, 17, 1
	v_bfi_b32 v37, v69, s49, v37
	v_bfe_i32 v69, v68, 18, 1
	v_bfi_b32 v38, v69, s49, v38
	v_bfe_i32 v69, v68, 19, 1
	v_bfi_b32 v39, v69, s49, v39
	v_bfe_i32 v69, v68, 20, 1
	v_bfi_b32 v40, v69, s49, v40
	v_bfe_i32 v69, v68, 21, 1
	v_bfi_b32 v41, v69, s49, v41
	v_bfe_i32 v69, v68, 22, 1
	v_bfi_b32 v42, v69, s49, v42
	v_bfe_i32 v69, v68, 23, 1
	v_bfi_b32 v43, v69, s49, v43
	v_bfe_i32 v69, v68, 24, 1
	v_bfi_b32 v44, v69, s49, v44
	v_bfe_i32 v69, v68, 25, 1
	v_bfi_b32 v45, v69, s49, v45
	v_bfe_i32 v69, v68, 26, 1
	v_bfi_b32 v46, v69, s49, v46
	v_bfe_i32 v69, v68, 27, 1
	v_bfi_b32 v47, v69, s49, v47
	v_bfe_i32 v69, v68, 28, 1
	v_bfi_b32 v48, v69, s49, v48
	v_bfe_i32 v69, v68, 29, 1
	v_bfi_b32 v49, v69, s49, v49
	v_bfe_i32 v69, v68, 30, 1
	v_bfi_b32 v50, v69, s49, v50
	v_bfe_i32 v69, v68, 31, 1
	v_bfi_b32 v51, v69, s49, v51
	s_nop 0
	v_max_f32_e32 v68, v53, v53
	v_max_f32_e32 v69, v52, v52
	v_max_f32_e32 v68, v69, v68
	v_max3_f32 v69, v54, v55, v37
	v_max3_f32 v68, v68, v36, v38
	v_max3_f32 v68, v68, v39, v56
	v_max3_f32 v69, v69, v58, v59
	v_max3_f32 v68, v68, v57, v40
	v_max3_f32 v69, v69, v42, v43
	v_max3_f32 v68, v68, v41, v60
	v_max3_f32 v69, v69, v62, v63
	v_max3_f32 v68, v68, v61, v44
	v_max3_f32 v69, v69, v46, v47
	v_max3_f32 v68, v68, v45, v64
	v_max3_f32 v69, v69, v66, v67
	v_max3_f32 v68, v68, v65, v48
	v_max3_f32 v69, v69, v50, v51
	v_max3_f32 v68, v68, v49, v69
	v_mov_b32_e32 v69, v68
	s_nop 1
	v_permlane32_swap_b32_e32 v68, v69
	v_max_f32_e32 v69, v69, v69
	v_max_f32_e32 v68, v68, v68
	v_max_f32_e32 v68, v68, v69
	v_cmp_lt_f32_e32 vcc, s51, v68
	s_cmp_lg_u64 vcc, 0
	s_cselect_b64 s[8:9], -1, 0
	s_cbranch_vccnz .LBB0_1910

.LBB0_1905:
	s_add_i32 s8, s4, 0x2000
	s_cmpk_lg_i32 s4, 0x4000
	s_cselect_b32 s60, s8, 0
	v_add_u32_e32 v183, s12, v199
	ds_read_b64_tr_b16 v[150:151], v183 offset:24576
	ds_read_b64_tr_b16 v[152:153], v183 offset:25088
	v_add_f32_e32 v72, v52, v53
	v_add_f32_e32 v72, v54, v72
	v_add_f32_e32 v72, v55, v72
	v_add_f32_e32 v72, v56, v72
	v_add_f32_e32 v88, v57, v72
	v_cvt_pk_bf16_f32 v118, v52, v53
	v_cvt_pk_bf16_f32 v119, v54, v55
	s_waitcnt lgkmcnt(9)
	v_mfma_f32_32x32x16_bf16 v[68:83], v[68:71], v[130:133], 0
	ds_read_b64_tr_b16 v[146:147], v183 offset:28672
	ds_read_b64_tr_b16 v[148:149], v183 offset:29184
	v_add_f32_e32 v52, v58, v88
	v_add_f32_e32 v52, v59, v52
	v_add_f32_e32 v52, v60, v52
	v_add_f32_e32 v52, v61, v52
	v_cvt_pk_bf16_f32 v120, v56, v57
	v_cvt_pk_bf16_f32 v121, v58, v59
	s_waitcnt lgkmcnt(10)
	v_mfma_f32_32x32x16_bf16 v[84:99], v[84:87], v[130:133], 0
	ds_read_b64_tr_b16 v[142:143], v183 offset:25600
	ds_read_b64_tr_b16 v[144:145], v183 offset:26112
	v_add_f32_e32 v52, v62, v52
	v_add_f32_e32 v52, v63, v52
	v_add_f32_e32 v52, v64, v52
	v_add_f32_e32 v52, v65, v52
	v_cvt_pk_bf16_f32 v110, v60, v61
	v_cvt_pk_bf16_f32 v111, v62, v63
	s_waitcnt lgkmcnt(11)
	v_mfma_f32_32x32x16_bf16 v[68:83], v[170:173], v[126:129], v[68:83]
	ds_read_b64_tr_b16 v[138:139], v183 offset:29696
	ds_read_b64_tr_b16 v[140:141], v183 offset:30208
	v_add_f32_e32 v52, v66, v52
	v_add_f32_e32 v52, v67, v52
	v_add_f32_e32 v52, v36, v52
	v_add_f32_e32 v52, v37, v52
	v_cvt_pk_bf16_f32 v112, v64, v65
	v_cvt_pk_bf16_f32 v113, v66, v67
	s_waitcnt lgkmcnt(12)
	v_mfma_f32_32x32x16_bf16 v[84:99], v[134:137], v[126:129], v[84:99]
	ds_read_b64_tr_b16 v[134:135], v183 offset:26624
	ds_read_b64_tr_b16 v[136:137], v183 offset:27136
	v_add_f32_e32 v52, v38, v52
	v_add_f32_e32 v52, v39, v52
	v_add_f32_e32 v52, v40, v52
	v_add_f32_e32 v52, v41, v52
	v_cvt_pk_bf16_f32 v106, v36, v37
	v_cvt_pk_bf16_f32 v107, v38, v39
	s_waitcnt lgkmcnt(13)
	v_mfma_f32_32x32x16_bf16 v[68:83], v[166:169], v[122:125], v[68:83]
	ds_read_b64_tr_b16 v[174:175], v183 offset:30720
	ds_read_b64_tr_b16 v[176:177], v183 offset:31232
	v_add_f32_e32 v36, v42, v52
	v_add_f32_e32 v36, v43, v36
	v_add_f32_e32 v36, v44, v36
	v_add_f32_e32 v36, v45, v36
	v_cvt_pk_bf16_f32 v108, v40, v41
	v_cvt_pk_bf16_f32 v109, v42, v43
	s_waitcnt lgkmcnt(14)
	v_mfma_f32_32x32x16_bf16 v[84:99], v[158:161], v[122:125], v[84:99]
	ds_read_b64_tr_b16 v[170:171], v183 offset:27648
	ds_read_b64_tr_b16 v[172:173], v183 offset:28160
	v_add_f32_e32 v36, v46, v36
	v_add_f32_e32 v36, v47, v36
	v_add_f32_e32 v36, v48, v36
	v_add_f32_e32 v36, v49, v36
	v_cvt_pk_bf16_f32 v102, v44, v45
	v_cvt_pk_bf16_f32 v103, v46, v47
	s_waitcnt lgkmcnt(14)
	v_mfma_f32_32x32x16_bf16 v[68:83], v[162:165], v[114:117], v[68:83]
	ds_read_b64_tr_b16 v[166:167], v183 offset:31744
	ds_read_b64_tr_b16 v[168:169], v183 offset:32256
	v_add_f32_e32 v36, v50, v36
	v_add_f32_e32 v36, v51, v36
	v_add_f32_e32 v158, 0, v36
	v_cvt_pk_bf16_f32 v104, v48, v49
	v_cvt_pk_bf16_f32 v105, v50, v51
	v_mfma_f32_32x32x16_bf16 v[84:99], v[154:157], v[114:117], v[84:99]
	v_lshl_add_u64 v[36:37], v[178:179], 0, s[36:37]
	s_add_i32 s8, s4, s57
	s_mov_b32 s9, m0
	s_mov_b32 m0, s8
	s_nop 0
	global_load_lds_dwordx4 v[36:37], off
	s_mov_b32 m0, s9
	v_lshl_add_u64 v[36:37], v[180:181], 0, s[30:31]
	s_add_i32 s8, s60, s58
	s_mov_b32 s9, m0
	s_mov_b32 m0, s8
	s_nop 0
	global_load_lds_dwordx4 v[36:37], off
	s_mov_b32 m0, s9
	v_sub_f32_e32 v52, v68, v211
	s_nop 6
	v_sub_f32_e32 v36, v84, v211
	v_sub_f32_e32 v53, v69, v211
	v_sub_f32_e32 v37, v85, v211
	v_sub_f32_e32 v54, v70, v211
	v_sub_f32_e32 v38, v86, v211
	v_sub_f32_e32 v55, v71, v211
	v_sub_f32_e32 v39, v87, v211
	v_sub_f32_e32 v56, v72, v211
	v_sub_f32_e32 v40, v88, v211
	v_sub_f32_e32 v57, v73, v211
	v_sub_f32_e32 v41, v89, v211
	v_sub_f32_e32 v58, v74, v211
	v_sub_f32_e32 v42, v90, v211
	v_sub_f32_e32 v59, v75, v211
	v_sub_f32_e32 v43, v91, v211
	v_sub_f32_e32 v60, v76, v211
	v_sub_f32_e32 v44, v92, v211
	v_sub_f32_e32 v61, v77, v211
	v_sub_f32_e32 v45, v93, v211
	v_sub_f32_e32 v62, v78, v211
	v_sub_f32_e32 v46, v94, v211
	v_sub_f32_e32 v63, v79, v211
	v_sub_f32_e32 v47, v95, v211
	v_sub_f32_e32 v64, v80, v211
	v_sub_f32_e32 v48, v96, v211
	v_sub_f32_e32 v65, v81, v211
	v_sub_f32_e32 v49, v97, v211
	v_sub_f32_e32 v66, v82, v211
	v_sub_f32_e32 v50, v98, v211
	v_sub_f32_e32 v67, v83, v211
	v_sub_f32_e32 v51, v99, v211
	ds_read_b32 v68, v182 offset:256
	s_waitcnt lgkmcnt(0)
	v_bfe_i32 v69, v68, 0, 1
	v_bfi_b32 v52, v69, s49, v52
	s_nop 0
	v_add_f32_e32 v213, v2, v158
	v_bfe_i32 v69, v68, 1, 1
	v_bfi_b32 v53, v69, s49, v53
	v_bfe_i32 v69, v68, 2, 1
	v_bfi_b32 v54, v69, s49, v54
	v_bfe_i32 v69, v68, 3, 1
	v_bfi_b32 v55, v69, s49, v55
	v_bfe_i32 v69, v68, 4, 1
	v_bfi_b32 v56, v69, s49, v56
	v_bfe_i32 v69, v68, 5, 1
	v_bfi_b32 v57, v69, s49, v57
	v_bfe_i32 v69, v68, 6, 1
	v_bfi_b32 v58, v69, s49, v58
	v_bfe_i32 v69, v68, 7, 1
	v_bfi_b32 v59, v69, s49, v59
	v_bfe_i32 v69, v68, 8, 1
	v_bfi_b32 v60, v69, s49, v60
	v_bfe_i32 v69, v68, 9, 1
	v_bfi_b32 v61, v69, s49, v61
	v_bfe_i32 v69, v68, 10, 1
	v_bfi_b32 v62, v69, s49, v62
	v_bfe_i32 v69, v68, 11, 1
	v_bfi_b32 v63, v69, s49, v63
	v_bfe_i32 v69, v68, 12, 1
	v_bfi_b32 v64, v69, s49, v64
	v_bfe_i32 v69, v68, 13, 1
	v_bfi_b32 v65, v69, s49, v65
	v_bfe_i32 v69, v68, 14, 1
	v_bfi_b32 v66, v69, s49, v66
	v_bfe_i32 v69, v68, 15, 1
	v_bfi_b32 v67, v69, s49, v67
	v_bfe_i32 v69, v68, 16, 1
	v_bfi_b32 v36, v69, s49, v36
	v_bfe_i32 v69, v68, 17, 1
	v_bfi_b32 v37, v69, s49, v37
	v_bfe_i32 v69, v68, 18, 1
	v_bfi_b32 v38, v69, s49, v38
	v_bfe_i32 v69, v68, 19, 1
	v_bfi_b32 v39, v69, s49, v39
	v_bfe_i32 v69, v68, 20, 1
	v_bfi_b32 v40, v69, s49, v40
	v_bfe_i32 v69, v68, 21, 1
	v_bfi_b32 v41, v69, s49, v41
	v_bfe_i32 v69, v68, 22, 1
	v_bfi_b32 v42, v69, s49, v42
	v_bfe_i32 v69, v68, 23, 1
	v_bfi_b32 v43, v69, s49, v43
	v_bfe_i32 v69, v68, 24, 1
	v_bfi_b32 v44, v69, s49, v44
	v_bfe_i32 v69, v68, 25, 1
	v_bfi_b32 v45, v69, s49, v45
	v_bfe_i32 v69, v68, 26, 1
	v_bfi_b32 v46, v69, s49, v46
	v_bfe_i32 v69, v68, 27, 1
	v_bfi_b32 v47, v69, s49, v47
	v_bfe_i32 v69, v68, 28, 1
	v_bfi_b32 v48, v69, s49, v48
	v_bfe_i32 v69, v68, 29, 1
	v_bfi_b32 v49, v69, s49, v49
	v_bfe_i32 v69, v68, 30, 1
	v_bfi_b32 v50, v69, s49, v50
	v_bfe_i32 v69, v68, 31, 1
	v_bfi_b32 v51, v69, s49, v51
	s_nop 0
	v_max_f32_e32 v68, v53, v53
	v_max_f32_e32 v69, v52, v52
	v_max_f32_e32 v68, v69, v68
	v_max3_f32 v69, v54, v55, v37
	v_max3_f32 v68, v68, v36, v38
	v_max3_f32 v68, v68, v39, v56
	v_max3_f32 v69, v69, v58, v59
	v_max3_f32 v68, v68, v57, v40
	v_max3_f32 v69, v69, v42, v43
	v_max3_f32 v68, v68, v41, v60
	v_max3_f32 v69, v69, v62, v63
	v_max3_f32 v68, v68, v61, v44
	v_max3_f32 v69, v69, v46, v47
	v_max3_f32 v68, v68, v45, v64
	v_max3_f32 v69, v69, v66, v67
	v_max3_f32 v68, v68, v65, v48
	v_max3_f32 v69, v69, v50, v51
	v_max3_f32 v2, v68, v49, v69
	v_mov_b32_e32 v68, v2
	s_nop 1
	v_permlane32_swap_b32_e32 v2, v68
	v_max_f32_e32 v68, v68, v68
	v_max_f32_e32 v2, v2, v2
	v_max_f32_e32 v2, v2, v68
	v_cmp_lt_f32_e32 vcc, s51, v2
	s_cmp_lg_u64 vcc, 0
	s_cselect_b64 s[8:9], -1, 0
	s_cbranch_vccnz .LBB0_1913

.LBB0_1920:
	v_lshl_add_u64 v[224:225], v[222:223], 0, s[8:9]
	v_add_f32_e32 v213, v213, v36
	v_lshl_add_u64 v[36:37], v[224:225], 0, s[26:27]
	s_add_i32 s2, s62, s58
	s_mov_b32 s3, m0
	s_mov_b32 m0, s2
	s_nop 0
	global_load_lds_dwordx4 v[36:37], off
	s_mov_b32 m0, s3
	v_add_u32_e32 v50, 0xffffff00, v2
	v_sub_f32_e32 v52, v68, v211
	v_sub_f32_e32 v36, v84, v211
	v_sub_f32_e32 v53, v69, v211
	v_sub_f32_e32 v37, v85, v211
	v_sub_f32_e32 v54, v70, v211
	v_sub_f32_e32 v38, v86, v211
	v_sub_f32_e32 v55, v71, v211
	v_sub_f32_e32 v39, v87, v211
	v_sub_f32_e32 v56, v72, v211
	v_sub_f32_e32 v40, v88, v211
	v_sub_f32_e32 v57, v73, v211
	v_sub_f32_e32 v41, v89, v211
	v_sub_f32_e32 v58, v74, v211
	v_sub_f32_e32 v42, v90, v211
	v_sub_f32_e32 v59, v75, v211
	v_sub_f32_e32 v43, v91, v211
	v_sub_f32_e32 v60, v76, v211
	v_sub_f32_e32 v44, v92, v211
	v_sub_f32_e32 v61, v77, v211
	v_sub_f32_e32 v45, v93, v211
	v_sub_f32_e32 v62, v78, v211
	v_sub_f32_e32 v46, v94, v211
	v_sub_f32_e32 v63, v79, v211
	v_sub_f32_e32 v47, v95, v211
	v_sub_f32_e32 v64, v80, v211
	v_sub_f32_e32 v48, v96, v211
	v_sub_f32_e32 v65, v81, v211
	v_sub_f32_e32 v49, v97, v211
	ds_read_b32 v68, v50
	v_sub_f32_e32 v66, v82, v211
	v_sub_f32_e32 v50, v98, v211
	v_sub_f32_e32 v67, v83, v211
	v_sub_f32_e32 v51, v99, v211
	s_waitcnt lgkmcnt(0)
	v_bfe_i32 v69, v68, 0, 1
	v_bfi_b32 v52, v69, s49, v52
	v_bfe_i32 v69, v68, 1, 1
	v_bfi_b32 v53, v69, s49, v53
	v_bfe_i32 v69, v68, 2, 1
	v_bfi_b32 v54, v69, s49, v54
	v_bfe_i32 v69, v68, 3, 1
	v_bfi_b32 v55, v69, s49, v55
	v_bfe_i32 v69, v68, 4, 1
	v_bfi_b32 v56, v69, s49, v56
	v_bfe_i32 v69, v68, 5, 1
	v_bfi_b32 v57, v69, s49, v57
	v_bfe_i32 v69, v68, 6, 1
	v_bfi_b32 v58, v69, s49, v58
	v_bfe_i32 v69, v68, 7, 1
	v_bfi_b32 v59, v69, s49, v59
	v_bfe_i32 v69, v68, 8, 1
	v_bfi_b32 v60, v69, s49, v60
	v_bfe_i32 v69, v68, 9, 1
	v_bfi_b32 v61, v69, s49, v61
	v_bfe_i32 v69, v68, 10, 1
	v_bfi_b32 v62, v69, s49, v62
	v_bfe_i32 v69, v68, 11, 1
	v_bfi_b32 v63, v69, s49, v63
	v_bfe_i32 v69, v68, 12, 1
	v_bfi_b32 v64, v69, s49, v64
	v_bfe_i32 v69, v68, 13, 1
	v_bfi_b32 v65, v69, s49, v65
	v_bfe_i32 v69, v68, 14, 1
	v_bfi_b32 v66, v69, s49, v66
	v_bfe_i32 v69, v68, 15, 1
	v_bfi_b32 v67, v69, s49, v67
	v_bfe_i32 v69, v68, 16, 1
	v_bfi_b32 v36, v69, s49, v36
	v_bfe_i32 v69, v68, 17, 1
	v_bfi_b32 v37, v69, s49, v37
	v_bfe_i32 v69, v68, 18, 1
	v_bfi_b32 v38, v69, s49, v38
	v_bfe_i32 v69, v68, 19, 1
	v_bfi_b32 v39, v69, s49, v39
	v_bfe_i32 v69, v68, 20, 1
	v_bfi_b32 v40, v69, s49, v40
	v_bfe_i32 v69, v68, 21, 1
	v_bfi_b32 v41, v69, s49, v41
	v_bfe_i32 v69, v68, 22, 1
	v_bfi_b32 v42, v69, s49, v42
	v_bfe_i32 v69, v68, 23, 1
	v_bfi_b32 v43, v69, s49, v43
	v_bfe_i32 v69, v68, 24, 1
	v_bfi_b32 v44, v69, s49, v44
	v_bfe_i32 v69, v68, 25, 1
	v_bfi_b32 v45, v69, s49, v45
	v_bfe_i32 v69, v68, 26, 1
	v_bfi_b32 v46, v69, s49, v46
	v_bfe_i32 v69, v68, 27, 1
	v_bfi_b32 v47, v69, s49, v47
	v_bfe_i32 v69, v68, 28, 1
	v_bfi_b32 v48, v69, s49, v48
	v_bfe_i32 v69, v68, 29, 1
	v_bfi_b32 v49, v69, s49, v49
	v_bfe_i32 v69, v68, 30, 1
	v_bfi_b32 v50, v69, s49, v50
	v_bfe_i32 v69, v68, 31, 1
	v_bfi_b32 v51, v69, s49, v51
	s_nop 0
	v_max_f32_e32 v68, v53, v53
	v_max_f32_e32 v69, v52, v52
	v_max_f32_e32 v68, v69, v68
	v_max3_f32 v69, v54, v55, v37
	v_max3_f32 v68, v68, v36, v38
	v_max3_f32 v68, v68, v39, v56
	v_max3_f32 v69, v69, v58, v59
	v_max3_f32 v68, v68, v57, v40
	v_max3_f32 v69, v69, v42, v43
	v_max3_f32 v68, v68, v41, v60
	v_max3_f32 v69, v69, v62, v63
	v_max3_f32 v68, v68, v61, v44
	v_max3_f32 v69, v69, v46, v47
	v_max3_f32 v68, v68, v45, v64
	v_max3_f32 v69, v69, v66, v67
	v_max3_f32 v68, v68, v65, v48
	v_max3_f32 v69, v69, v50, v51
	v_max3_f32 v68, v68, v49, v69
	v_mov_b32_e32 v69, v68
	s_nop 1
	v_permlane32_swap_b32_e32 v68, v69
	v_max_f32_e32 v69, v69, v69
	v_max_f32_e32 v68, v68, v68
	v_max_f32_e32 v68, v68, v69
	v_cmp_lt_f32_e32 vcc, s51, v68
	s_cmp_lg_u64 vcc, 0
	s_cselect_b64 s[2:3], -1, 0
	s_cbranch_vccnz .LBB0_1956

.LBB0_1933:
	v_add_f32_e32 v213, v213, v36
	v_sub_f32_e32 v52, v68, v211
	v_sub_f32_e32 v36, v84, v211
	v_sub_f32_e32 v53, v69, v211
	v_sub_f32_e32 v37, v85, v211
	v_sub_f32_e32 v54, v70, v211
	v_sub_f32_e32 v38, v86, v211
	v_sub_f32_e32 v55, v71, v211
	v_sub_f32_e32 v39, v87, v211
	v_sub_f32_e32 v56, v72, v211
	v_sub_f32_e32 v40, v88, v211
	v_sub_f32_e32 v57, v73, v211
	v_sub_f32_e32 v41, v89, v211
	v_sub_f32_e32 v58, v74, v211
	v_sub_f32_e32 v42, v90, v211
	v_sub_f32_e32 v59, v75, v211
	v_sub_f32_e32 v43, v91, v211
	v_sub_f32_e32 v60, v76, v211
	v_sub_f32_e32 v44, v92, v211
	v_sub_f32_e32 v61, v77, v211
	v_sub_f32_e32 v45, v93, v211
	v_sub_f32_e32 v62, v78, v211
	v_sub_f32_e32 v46, v94, v211
	v_sub_f32_e32 v63, v79, v211
	v_sub_f32_e32 v47, v95, v211
	v_sub_f32_e32 v64, v80, v211
	v_sub_f32_e32 v48, v96, v211
	v_sub_f32_e32 v65, v81, v211
	v_sub_f32_e32 v49, v97, v211
	v_sub_f32_e32 v66, v82, v211
	v_sub_f32_e32 v50, v98, v211
	v_sub_f32_e32 v67, v83, v211
	v_sub_f32_e32 v51, v99, v211
	ds_read_b32 v68, v2
	s_waitcnt lgkmcnt(0)
	v_bfe_i32 v69, v68, 0, 1
	v_bfi_b32 v52, v69, s49, v52
	v_bfe_i32 v69, v68, 1, 1
	v_bfi_b32 v53, v69, s49, v53
	v_bfe_i32 v69, v68, 2, 1
	v_bfi_b32 v54, v69, s49, v54
	v_bfe_i32 v69, v68, 3, 1
	v_bfi_b32 v55, v69, s49, v55
	v_bfe_i32 v69, v68, 4, 1
	v_bfi_b32 v56, v69, s49, v56
	v_bfe_i32 v69, v68, 5, 1
	v_bfi_b32 v57, v69, s49, v57
	v_bfe_i32 v69, v68, 6, 1
	v_bfi_b32 v58, v69, s49, v58
	v_bfe_i32 v69, v68, 7, 1
	v_bfi_b32 v59, v69, s49, v59
	v_bfe_i32 v69, v68, 8, 1
	v_bfi_b32 v60, v69, s49, v60
	v_bfe_i32 v69, v68, 9, 1
	v_bfi_b32 v61, v69, s49, v61
	v_bfe_i32 v69, v68, 10, 1
	v_bfi_b32 v62, v69, s49, v62
	v_bfe_i32 v69, v68, 11, 1
	v_bfi_b32 v63, v69, s49, v63
	v_bfe_i32 v69, v68, 12, 1
	v_bfi_b32 v64, v69, s49, v64
	v_bfe_i32 v69, v68, 13, 1
	v_bfi_b32 v65, v69, s49, v65
	v_bfe_i32 v69, v68, 14, 1
	v_bfi_b32 v66, v69, s49, v66
	v_bfe_i32 v69, v68, 15, 1
	v_bfi_b32 v67, v69, s49, v67
	v_bfe_i32 v69, v68, 16, 1
	v_bfi_b32 v36, v69, s49, v36
	v_bfe_i32 v69, v68, 17, 1
	v_bfi_b32 v37, v69, s49, v37
	v_bfe_i32 v69, v68, 18, 1
	v_bfi_b32 v38, v69, s49, v38
	v_bfe_i32 v69, v68, 19, 1
	v_bfi_b32 v39, v69, s49, v39
	v_bfe_i32 v69, v68, 20, 1
	v_bfi_b32 v40, v69, s49, v40
	v_bfe_i32 v69, v68, 21, 1
	v_bfi_b32 v41, v69, s49, v41
	v_bfe_i32 v69, v68, 22, 1
	v_bfi_b32 v42, v69, s49, v42
	v_bfe_i32 v69, v68, 23, 1
	v_bfi_b32 v43, v69, s49, v43
	v_bfe_i32 v69, v68, 24, 1
	v_bfi_b32 v44, v69, s49, v44
	v_bfe_i32 v69, v68, 25, 1
	v_bfi_b32 v45, v69, s49, v45
	v_bfe_i32 v69, v68, 26, 1
	v_bfi_b32 v46, v69, s49, v46
	v_bfe_i32 v69, v68, 27, 1
	v_bfi_b32 v47, v69, s49, v47
	v_bfe_i32 v69, v68, 28, 1
	v_bfi_b32 v48, v69, s49, v48
	v_bfe_i32 v69, v68, 29, 1
	v_bfi_b32 v49, v69, s49, v49
	v_bfe_i32 v69, v68, 30, 1
	v_bfi_b32 v50, v69, s49, v50
	v_bfe_i32 v69, v68, 31, 1
	v_bfi_b32 v51, v69, s49, v51
	s_nop 0
	v_max_f32_e32 v68, v53, v53
	v_max_f32_e32 v69, v52, v52
	v_max_f32_e32 v68, v69, v68
	v_max3_f32 v69, v54, v55, v37
	v_max3_f32 v68, v68, v36, v38
	v_max3_f32 v68, v68, v39, v56
	v_max3_f32 v69, v69, v58, v59
	v_max3_f32 v68, v68, v57, v40
	v_max3_f32 v69, v69, v42, v43
	v_max3_f32 v68, v68, v41, v60
	v_max3_f32 v69, v69, v62, v63
	v_max3_f32 v68, v68, v61, v44
	v_max3_f32 v69, v69, v46, v47
	v_max3_f32 v68, v68, v45, v64
	v_max3_f32 v69, v69, v66, v67
	v_max3_f32 v68, v68, v65, v48
	v_max3_f32 v69, v69, v50, v51
	v_max3_f32 v68, v68, v49, v69
	v_mov_b32_e32 v69, v68
	s_nop 1
	v_permlane32_swap_b32_e32 v68, v69
	v_max_f32_e32 v69, v69, v69
	v_max_f32_e32 v68, v68, v68
	v_max_f32_e32 v68, v68, v69
	v_cmp_lt_f32_e32 vcc, s51, v68
	s_cmp_lg_u64 vcc, 0
	s_cselect_b64 s[12:13], -1, 0
	s_cbranch_vccnz .LBB0_1959

.LBB0_1964:
	v_add_u32_e32 v2, s62, v199
	ds_read_b64_tr_b16 v[166:167], v2 offset:24576
	ds_read_b64_tr_b16 v[168:169], v2 offset:25088
	v_add_f32_e32 v68, v52, v53
	v_add_f32_e32 v68, v54, v68
	v_add_f32_e32 v68, v55, v68
	v_add_f32_e32 v68, v56, v68
	v_add_f32_e32 v84, v57, v68
	s_waitcnt lgkmcnt(3)
	v_mfma_f32_32x32x16_bf16 v[68:83], v[162:165], v[130:133], 0
	v_cvt_pk_bf16_f32 v118, v52, v53
	v_cvt_pk_bf16_f32 v119, v54, v55
	ds_read_b64_tr_b16 v[162:163], v2 offset:28672
	ds_read_b64_tr_b16 v[164:165], v2 offset:29184
	v_add_f32_e32 v52, v58, v84
	v_add_f32_e32 v52, v59, v52
	v_add_f32_e32 v52, v60, v52
	v_add_f32_e32 v52, v61, v52
	v_cvt_pk_bf16_f32 v120, v56, v57
	v_cvt_pk_bf16_f32 v121, v58, v59
	s_waitcnt lgkmcnt(4)
	v_mfma_f32_32x32x16_bf16 v[84:99], v[158:161], v[130:133], 0
	ds_read_b64_tr_b16 v[158:159], v2 offset:25600
	ds_read_b64_tr_b16 v[160:161], v2 offset:26112
	v_mfma_f32_32x32x16_bf16 v[68:83], v[154:157], v[126:129], v[68:83]
	v_add_f32_e32 v52, v62, v52
	v_add_f32_e32 v52, v63, v52
	v_add_f32_e32 v52, v64, v52
	v_add_f32_e32 v52, v65, v52
	v_cvt_pk_bf16_f32 v110, v60, v61
	v_cvt_pk_bf16_f32 v111, v62, v63
	ds_read_b64_tr_b16 v[154:155], v2 offset:29696
	ds_read_b64_tr_b16 v[156:157], v2 offset:30208
	v_add_f32_e32 v52, v66, v52
	v_add_f32_e32 v52, v67, v52
	v_add_f32_e32 v52, v36, v52
	v_add_f32_e32 v52, v37, v52
	v_cvt_pk_bf16_f32 v112, v64, v65
	v_cvt_pk_bf16_f32 v113, v66, v67
	v_mfma_f32_32x32x16_bf16 v[84:99], v[150:153], v[126:129], v[84:99]
	ds_read_b64_tr_b16 v[150:151], v2 offset:26624
	ds_read_b64_tr_b16 v[152:153], v2 offset:27136
	v_mfma_f32_32x32x16_bf16 v[68:83], v[146:149], v[122:125], v[68:83]
	v_add_f32_e32 v52, v38, v52
	v_add_f32_e32 v52, v39, v52
	v_add_f32_e32 v52, v40, v52
	v_add_f32_e32 v52, v41, v52
	v_cvt_pk_bf16_f32 v106, v36, v37
	v_cvt_pk_bf16_f32 v107, v38, v39
	ds_read_b64_tr_b16 v[130:131], v2 offset:30720
	ds_read_b64_tr_b16 v[132:133], v2 offset:31232
	v_add_f32_e32 v36, v42, v52
	v_add_f32_e32 v36, v43, v36
	v_add_f32_e32 v36, v44, v36
	v_add_f32_e32 v36, v45, v36
	v_cvt_pk_bf16_f32 v108, v40, v41
	v_cvt_pk_bf16_f32 v109, v42, v43
	v_mfma_f32_32x32x16_bf16 v[84:99], v[142:145], v[122:125], v[84:99]
	ds_read_b64_tr_b16 v[126:127], v2 offset:27648
	ds_read_b64_tr_b16 v[128:129], v2 offset:28160
	v_mfma_f32_32x32x16_bf16 v[68:83], v[138:141], v[114:117], v[68:83]
	v_add_f32_e32 v36, v46, v36
	v_add_f32_e32 v36, v47, v36
	v_add_f32_e32 v36, v48, v36
	v_add_f32_e32 v36, v49, v36
	v_cvt_pk_bf16_f32 v102, v44, v45
	v_cvt_pk_bf16_f32 v103, v46, v47
	ds_read_b64_tr_b16 v[122:123], v2 offset:31744
	ds_read_b64_tr_b16 v[124:125], v2 offset:32256
	v_add_f32_e32 v2, v50, v36
	v_add_f32_e32 v2, v51, v2
	v_add_f32_e32 v2, 0, v2
	v_cvt_pk_bf16_f32 v104, v48, v49
	v_cvt_pk_bf16_f32 v105, v50, v51
	v_mfma_f32_32x32x16_bf16 v[84:99], v[134:137], v[114:117], v[84:99]
	v_lshl_add_u32 v50, s56, 2, v209
	v_sub_f32_e32 v52, v68, v211
	s_nop 9
	v_sub_f32_e32 v36, v84, v211
	v_sub_f32_e32 v53, v69, v211
	v_sub_f32_e32 v37, v85, v211
	v_sub_f32_e32 v54, v70, v211
	v_sub_f32_e32 v38, v86, v211
	v_sub_f32_e32 v55, v71, v211
	v_sub_f32_e32 v39, v87, v211
	v_sub_f32_e32 v56, v72, v211
	v_sub_f32_e32 v40, v88, v211
	v_sub_f32_e32 v57, v73, v211
	v_sub_f32_e32 v41, v89, v211
	v_sub_f32_e32 v58, v74, v211
	v_sub_f32_e32 v42, v90, v211
	v_sub_f32_e32 v59, v75, v211
	v_sub_f32_e32 v43, v91, v211
	v_sub_f32_e32 v60, v76, v211
	v_sub_f32_e32 v44, v92, v211
	v_sub_f32_e32 v61, v77, v211
	v_sub_f32_e32 v45, v93, v211
	v_sub_f32_e32 v62, v78, v211
	v_sub_f32_e32 v46, v94, v211
	v_sub_f32_e32 v63, v79, v211
	v_sub_f32_e32 v47, v95, v211
	v_sub_f32_e32 v64, v80, v211
	v_sub_f32_e32 v48, v96, v211
	v_sub_f32_e32 v65, v81, v211
	v_sub_f32_e32 v49, v97, v211
	ds_read_b32 v68, v50 offset:768
	v_sub_f32_e32 v66, v82, v211
	v_sub_f32_e32 v50, v98, v211
	v_sub_f32_e32 v67, v83, v211
	v_sub_f32_e32 v51, v99, v211
	s_waitcnt lgkmcnt(0)
	v_bfe_i32 v69, v68, 0, 1
	v_bfi_b32 v52, v69, s49, v52
	s_nop 0
	v_add_f32_e32 v2, v213, v2
	v_bfe_i32 v69, v68, 1, 1
	v_bfi_b32 v53, v69, s49, v53
	v_bfe_i32 v69, v68, 2, 1
	v_bfi_b32 v54, v69, s49, v54
	v_bfe_i32 v69, v68, 3, 1
	v_bfi_b32 v55, v69, s49, v55
	v_bfe_i32 v69, v68, 4, 1
	v_bfi_b32 v56, v69, s49, v56
	v_bfe_i32 v69, v68, 5, 1
	v_bfi_b32 v57, v69, s49, v57
	v_bfe_i32 v69, v68, 6, 1
	v_bfi_b32 v58, v69, s49, v58
	v_bfe_i32 v69, v68, 7, 1
	v_bfi_b32 v59, v69, s49, v59
	v_bfe_i32 v69, v68, 8, 1
	v_bfi_b32 v60, v69, s49, v60
	v_bfe_i32 v69, v68, 9, 1
	v_bfi_b32 v61, v69, s49, v61
	v_bfe_i32 v69, v68, 10, 1
	v_bfi_b32 v62, v69, s49, v62
	v_bfe_i32 v69, v68, 11, 1
	v_bfi_b32 v63, v69, s49, v63
	v_bfe_i32 v69, v68, 12, 1
	v_bfi_b32 v64, v69, s49, v64
	v_bfe_i32 v69, v68, 13, 1
	v_bfi_b32 v65, v69, s49, v65
	v_bfe_i32 v69, v68, 14, 1
	v_bfi_b32 v66, v69, s49, v66
	v_bfe_i32 v69, v68, 15, 1
	v_bfi_b32 v67, v69, s49, v67
	v_bfe_i32 v69, v68, 16, 1
	v_bfi_b32 v36, v69, s49, v36
	v_bfe_i32 v69, v68, 17, 1
	v_bfi_b32 v37, v69, s49, v37
	v_bfe_i32 v69, v68, 18, 1
	v_bfi_b32 v38, v69, s49, v38
	v_bfe_i32 v69, v68, 19, 1
	v_bfi_b32 v39, v69, s49, v39
	v_bfe_i32 v69, v68, 20, 1
	v_bfi_b32 v40, v69, s49, v40
	v_bfe_i32 v69, v68, 21, 1
	v_bfi_b32 v41, v69, s49, v41
	v_bfe_i32 v69, v68, 22, 1
	v_bfi_b32 v42, v69, s49, v42
	v_bfe_i32 v69, v68, 23, 1
	v_bfi_b32 v43, v69, s49, v43
	v_bfe_i32 v69, v68, 24, 1
	v_bfi_b32 v44, v69, s49, v44
	v_bfe_i32 v69, v68, 25, 1
	v_bfi_b32 v45, v69, s49, v45
	v_bfe_i32 v69, v68, 26, 1
	v_bfi_b32 v46, v69, s49, v46
	v_bfe_i32 v69, v68, 27, 1
	v_bfi_b32 v47, v69, s49, v47
	v_bfe_i32 v69, v68, 28, 1
	v_bfi_b32 v48, v69, s49, v48
	v_bfe_i32 v69, v68, 29, 1
	v_bfi_b32 v49, v69, s49, v49
	v_bfe_i32 v69, v68, 30, 1
	v_bfi_b32 v50, v69, s49, v50
	v_bfe_i32 v69, v68, 31, 1
	v_bfi_b32 v51, v69, s49, v51
	s_nop 0
	v_max_f32_e32 v68, v53, v53
	v_max_f32_e32 v69, v52, v52
	v_max_f32_e32 v68, v69, v68
	v_max3_f32 v69, v54, v55, v37
	v_max3_f32 v68, v68, v36, v38
	v_max3_f32 v68, v68, v39, v56
	v_max3_f32 v69, v69, v58, v59
	v_max3_f32 v68, v68, v57, v40
	v_max3_f32 v69, v69, v42, v43
	v_max3_f32 v68, v68, v41, v60
	v_max3_f32 v69, v69, v62, v63
	v_max3_f32 v68, v68, v61, v44
	v_max3_f32 v69, v69, v46, v47
	v_max3_f32 v68, v68, v45, v64
	v_max3_f32 v69, v69, v66, v67
	v_max3_f32 v68, v68, v65, v48
	v_max3_f32 v69, v69, v50, v51
	v_max3_f32 v68, v68, v49, v69
	v_mov_b32_e32 v69, v68
	s_nop 1
	v_permlane32_swap_b32_e32 v68, v69
	v_max_f32_e32 v69, v69, v69
	v_max_f32_e32 v68, v68, v68
	v_max_f32_e32 v68, v68, v69
	v_cmp_lt_f32_e32 vcc, s51, v68
	s_cmp_lg_u64 vcc, 0
	s_cselect_b64 s[2:3], -1, 0
	s_cbranch_vccnz .LBB0_1969
